# grid barrier: XCD leader no longer bumps the unused per-XCD generation word
# speedup vs baseline: 1.0053x; 1.0053x over previous
.LBB0_364:
	s_or_b64 exec, exec, s[8:9]
	s_mov_b64 s[8:9], exec
	v_mbcnt_lo_u32_b32 v0, s8, 0
	v_mbcnt_hi_u32_b32 v0, s9, v0
	v_cmp_eq_u32_e32 vcc, 0, v0
	s_waitcnt vmcnt(0)
	buffer_inv sc1
	s_and_saveexec_b64 s[12:13], vcc
	s_cbranch_execz .LBB0_366
	s_bcnt1_i32_b64 s1, s[8:9]
	v_mov_b32_e32 v0, 0x2000
	v_mov_b32_e32 v1, s1
.LBB0_366:
	s_or_b64 exec, exec, s[12:13]
	s_waitcnt vmcnt(0)

.LBB0_427:
	s_or_b64 exec, exec, s[6:7]
	s_mov_b64 s[6:7], exec
	v_mbcnt_lo_u32_b32 v0, s6, 0
	v_mbcnt_hi_u32_b32 v0, s7, v0
	v_cmp_eq_u32_e32 vcc, 0, v0
	s_waitcnt vmcnt(0)
	buffer_inv sc1
	s_and_saveexec_b64 s[10:11], vcc
	s_cbranch_execz .LBB0_429
	s_bcnt1_i32_b64 s0, s[6:7]
	v_mov_b32_e32 v0, s0
	v_mov_b32_e32 v2, 0x2000
.LBB0_429:
	s_or_b64 exec, exec, s[10:11]
	s_waitcnt vmcnt(0)

.LBB0_603:
	s_or_b64 exec, exec, s[6:7]
	s_mov_b64 s[6:7], exec
	v_mbcnt_lo_u32_b32 v0, s6, 0
	v_mbcnt_hi_u32_b32 v0, s7, v0
	v_cmp_eq_u32_e32 vcc, 0, v0
	s_waitcnt vmcnt(0)
	buffer_inv sc1
	s_and_saveexec_b64 s[10:11], vcc
	s_cbranch_execz .LBB0_605
	s_bcnt1_i32_b64 s0, s[6:7]
	v_mov_b32_e32 v0, s0
	v_mov_b32_e32 v2, 0x2000
.LBB0_605:
	s_or_b64 exec, exec, s[10:11]
	s_waitcnt vmcnt(0)

.LBB0_695:
	s_or_b64 exec, exec, s[6:7]
	s_mov_b64 s[6:7], exec
	v_mbcnt_lo_u32_b32 v0, s6, 0
	v_mbcnt_hi_u32_b32 v0, s7, v0
	v_cmp_eq_u32_e32 vcc, 0, v0
	s_waitcnt vmcnt(0)
	buffer_inv sc1
	s_and_saveexec_b64 s[10:11], vcc
	s_cbranch_execz .LBB0_697
	s_bcnt1_i32_b64 s0, s[6:7]
	v_mov_b32_e32 v0, s0
	v_mov_b32_e32 v2, 0x2000
.LBB0_697:
	s_or_b64 exec, exec, s[10:11]
	s_waitcnt vmcnt(0)

.LBB0_750:
	s_or_b64 exec, exec, s[6:7]
	s_mov_b64 s[6:7], exec
	v_mbcnt_lo_u32_b32 v0, s6, 0
	v_mbcnt_hi_u32_b32 v0, s7, v0
	v_cmp_eq_u32_e32 vcc, 0, v0
	s_waitcnt vmcnt(0)
	buffer_inv sc1
	s_and_saveexec_b64 s[10:11], vcc
	s_cbranch_execz .LBB0_752
	s_bcnt1_i32_b64 s0, s[6:7]
	v_mov_b32_e32 v0, s0
	v_mov_b32_e32 v2, 0x2000
.LBB0_752:
	s_or_b64 exec, exec, s[10:11]
	s_waitcnt vmcnt(0)

.LBB0_943:
	s_or_b64 exec, exec, s[6:7]
	s_mov_b64 s[6:7], exec
	v_mbcnt_lo_u32_b32 v0, s6, 0
	v_mbcnt_hi_u32_b32 v0, s7, v0
	v_cmp_eq_u32_e32 vcc, 0, v0
	s_waitcnt vmcnt(0)
	buffer_inv sc1
	s_and_saveexec_b64 s[10:11], vcc
	s_cbranch_execz .LBB0_945
	s_bcnt1_i32_b64 s0, s[6:7]
	v_mov_b32_e32 v0, s0
	v_mov_b32_e32 v2, 0x2000
.LBB0_945:
	s_or_b64 exec, exec, s[10:11]
	s_waitcnt vmcnt(0)

.LBB0_1281:
	s_or_b64 exec, exec, s[6:7]
	s_mov_b64 s[6:7], exec
	v_mbcnt_lo_u32_b32 v0, s6, 0
	v_mbcnt_hi_u32_b32 v0, s7, v0
	v_cmp_eq_u32_e32 vcc, 0, v0
	s_waitcnt vmcnt(0)
	buffer_inv sc1
	s_and_saveexec_b64 s[10:11], vcc
	s_cbranch_execz .LBB0_1283
	s_bcnt1_i32_b64 s0, s[6:7]
	v_mov_b32_e32 v0, s0
	v_mov_b32_e32 v2, 0x2000
.LBB0_1283:
	s_or_b64 exec, exec, s[10:11]
	s_waitcnt vmcnt(0)

.LBB0_1392:
	s_or_b64 exec, exec, s[8:9]
	s_mov_b64 s[8:9], exec
	v_mbcnt_lo_u32_b32 v0, s8, 0
	v_mbcnt_hi_u32_b32 v0, s9, v0
	v_cmp_eq_u32_e32 vcc, 0, v0
	s_waitcnt vmcnt(0)
	buffer_inv sc1
	s_and_saveexec_b64 s[14:15], vcc
	s_cbranch_execz .LBB0_1394
	s_bcnt1_i32_b64 s0, s[8:9]
	v_mov_b32_e32 v0, s0
	v_mov_b32_e32 v2, 0x2000
.LBB0_1394:
	s_or_b64 exec, exec, s[14:15]
	s_waitcnt vmcnt(0)

.LBB0_1450:
	s_or_b64 exec, exec, s[6:7]
	s_mov_b64 s[6:7], exec
	v_mbcnt_lo_u32_b32 v0, s6, 0
	v_mbcnt_hi_u32_b32 v0, s7, v0
	v_cmp_eq_u32_e32 vcc, 0, v0
	s_waitcnt vmcnt(0)
	buffer_inv sc1
	s_and_saveexec_b64 s[10:11], vcc
	s_cbranch_execz .LBB0_1452
	s_bcnt1_i32_b64 s0, s[6:7]
	v_mov_b32_e32 v0, s0
	v_mov_b32_e32 v2, 0x2000
.LBB0_1452:
	s_or_b64 exec, exec, s[10:11]
	s_waitcnt vmcnt(0)

.LBB0_1534:
	s_or_b64 exec, exec, s[6:7]
	s_mov_b64 s[6:7], exec
	v_mbcnt_lo_u32_b32 v0, s6, 0
	v_mbcnt_hi_u32_b32 v0, s7, v0
	v_cmp_eq_u32_e32 vcc, 0, v0
	s_waitcnt vmcnt(0)
	buffer_inv sc1
	s_and_saveexec_b64 s[10:11], vcc
	s_cbranch_execz .LBB0_1536
	s_bcnt1_i32_b64 s0, s[6:7]
	v_mov_b32_e32 v0, s0
	v_mov_b32_e32 v2, 0x2000
.LBB0_1536:
	s_or_b64 exec, exec, s[10:11]
	s_waitcnt vmcnt(0)

.LBB0_1589:
	s_or_b64 exec, exec, s[6:7]
	s_mov_b64 s[6:7], exec
	v_mbcnt_lo_u32_b32 v0, s6, 0
	v_mbcnt_hi_u32_b32 v0, s7, v0
	v_cmp_eq_u32_e32 vcc, 0, v0
	s_waitcnt vmcnt(0)
	buffer_inv sc1
	s_and_saveexec_b64 s[10:11], vcc
	s_cbranch_execz .LBB0_1591
	s_bcnt1_i32_b64 s0, s[6:7]
	v_mov_b32_e32 v0, s0
	v_mov_b32_e32 v2, 0x2000
.LBB0_1591:
	s_or_b64 exec, exec, s[10:11]
	s_waitcnt vmcnt(0)

.LBB0_1773:
	s_or_b64 exec, exec, s[6:7]
	s_mov_b64 s[6:7], exec
	v_mbcnt_lo_u32_b32 v0, s6, 0
	v_mbcnt_hi_u32_b32 v0, s7, v0
	v_cmp_eq_u32_e32 vcc, 0, v0
	s_waitcnt vmcnt(0)
	buffer_inv sc1
	s_and_saveexec_b64 s[10:11], vcc
	s_cbranch_execz .LBB0_1775
	s_bcnt1_i32_b64 s0, s[6:7]
	v_mov_b32_e32 v0, s0
	v_mov_b32_e32 v2, 0x2000
.LBB0_1775:
	s_or_b64 exec, exec, s[10:11]
	s_waitcnt vmcnt(0)

.LBB0_1860:
	s_bcnt1_i32_b64 s0, s[6:7]
	v_mov_b32_e32 v0, s0
	v_mov_b32_e32 v2, 0x2000
	s_getpc_b64 s[98:99]
